# G3 K-loop: first iteration peeled so each accumulator's first MFMA takes C=0; the 128 v_mov accumulator zeroing per unit deleted
# speedup vs baseline: 1.0122x; 1.0122x over previous
.LBB0_959:
	s_ashr_i32 s29, s28, 31
	s_lshl_b64 s[38:39], s[28:29], 19
	s_add_u32 s38, s16, s38
	s_addc_u32 s39, s17, s39
	s_and_b64 s[40:41], s[0:1], exec
	s_cselect_b32 s29, s39, s15
	s_cselect_b32 s54, s38, s14
	s_ashr_i32 s13, s12, 31
	s_lshl_b64 s[40:41], s[12:13], 19
	s_add_u32 s40, s18, s40
	s_addc_u32 s41, s19, s41
	s_and_b64 s[46:47], s[0:1], exec
	s_cselect_b32 s13, s41, s43
	s_cselect_b32 s55, s40, s42
	s_add_u32 s60, s42, 0x100
	s_addc_u32 s61, s43, 0
	s_add_u32 s42, s14, 0x40080
	s_addc_u32 s43, s15, 0
	s_mov_b32 s63, -2
	s_add_u32 s14, s42, 0xfffc0080
	s_addc_u32 s15, s43, -1
	s_add_i32 s24, 0, 0x10000
	s_cmp_eq_u32 s63, 12
	s_cselect_b32 s47, s29, s15
	s_cselect_b32 s46, s54, s14
	s_cselect_b32 s15, s13, s61
	s_cselect_b32 s14, s55, s60
	s_add_i32 s25, 0, 0x14000
	v_add_u32_e32 v172, s24, v145
	v_add_u32_e32 v188, s25, v145
	ds_read_b128 v[140:143], v172
	ds_read_b128 v[148:151], v172 offset:1024
	ds_read_b128 v[152:155], v172 offset:2048
	ds_read_b128 v[172:175], v172 offset:3072
	ds_read_b128 v[176:179], v188
	ds_read_b128 v[180:183], v188 offset:1024
	ds_read_b128 v[184:187], v188 offset:2048
	ds_read_b128 v[188:191], v188 offset:3072
	v_lshl_add_u64 v[192:193], s[42:43], 0, v[138:139]
	s_add_i32 m0, s21, 0xc000
	ds_read_b128 v[200:203], v147
	ds_read_b128 v[204:207], v147 offset:1024
	ds_read_b128 v[208:211], v147 offset:2048
	ds_read_b128 v[212:215], v147 offset:3072
	ds_read_b128 v[216:219], v147 offset:4096
	ds_read_b128 v[220:223], v147 offset:5120
	ds_read_b128 v[224:227], v147 offset:6144
	ds_read_b128 v[228:231], v147 offset:7168
	global_load_lds_dwordx4 v[192:193], off
	v_lshl_add_u64 v[192:193], s[42:43], 0, v[136:137]
	s_add_i32 m0, s21, 0xe000
	s_nop 0
	global_load_lds_dwordx4 v[192:193], off
	s_waitcnt vmcnt(8)
	s_waitcnt lgkmcnt(0)
	s_barrier
	s_setprio 1
	s_waitcnt lgkmcnt(0)
	v_mfma_f32_16x16x32_bf16 v[124:127], v[140:143], v[200:203], 0
	v_mfma_f32_16x16x32_bf16 v[116:119], v[152:155], v[200:203], 0
	v_mfma_f32_16x16x32_bf16 v[108:111], v[140:143], v[208:211], 0
	v_mfma_f32_16x16x32_bf16 v[104:107], v[152:155], v[208:211], 0
	v_mfma_f32_16x16x32_bf16 v[92:95], v[140:143], v[216:219], 0
	v_mfma_f32_16x16x32_bf16 v[88:91], v[152:155], v[216:219], 0
	v_mfma_f32_16x16x32_bf16 v[76:79], v[140:143], v[224:227], 0
	v_mfma_f32_16x16x32_bf16 v[72:75], v[152:155], v[224:227], 0
	v_mfma_f32_16x16x32_bf16 v[124:127], v[148:151], v[204:207], v[124:127]
	v_mfma_f32_16x16x32_bf16 v[116:119], v[172:175], v[204:207], v[116:119]
	v_mfma_f32_16x16x32_bf16 v[108:111], v[148:151], v[212:215], v[108:111]
	v_mfma_f32_16x16x32_bf16 v[104:107], v[172:175], v[212:215], v[104:107]
	v_mfma_f32_16x16x32_bf16 v[92:95], v[148:151], v[220:223], v[92:95]
	v_mfma_f32_16x16x32_bf16 v[88:91], v[172:175], v[220:223], v[88:91]
	v_mfma_f32_16x16x32_bf16 v[76:79], v[148:151], v[228:231], v[76:79]
	v_mfma_f32_16x16x32_bf16 v[72:75], v[172:175], v[228:231], v[72:75]
	s_setprio 0
	s_setprio 1
	v_mfma_f32_16x16x32_bf16 v[128:131], v[176:179], v[200:203], 0
	v_mfma_f32_16x16x32_bf16 v[120:123], v[184:187], v[200:203], 0
	v_mfma_f32_16x16x32_bf16 v[112:115], v[176:179], v[208:211], 0
	v_mfma_f32_16x16x32_bf16 v[100:103], v[184:187], v[208:211], 0
	v_mfma_f32_16x16x32_bf16 v[96:99], v[176:179], v[216:219], 0
	v_mfma_f32_16x16x32_bf16 v[84:87], v[184:187], v[216:219], 0
	v_mfma_f32_16x16x32_bf16 v[80:83], v[176:179], v[224:227], 0
	v_mfma_f32_16x16x32_bf16 v[68:71], v[184:187], v[224:227], 0
	v_mfma_f32_16x16x32_bf16 v[128:131], v[180:183], v[204:207], v[128:131]
	v_mfma_f32_16x16x32_bf16 v[120:123], v[188:191], v[204:207], v[120:123]
	v_mfma_f32_16x16x32_bf16 v[112:115], v[180:183], v[212:215], v[112:115]
	v_mfma_f32_16x16x32_bf16 v[100:103], v[188:191], v[212:215], v[100:103]
	v_mfma_f32_16x16x32_bf16 v[96:99], v[180:183], v[220:223], v[96:99]
	v_mfma_f32_16x16x32_bf16 v[84:87], v[188:191], v[220:223], v[84:87]
	v_mfma_f32_16x16x32_bf16 v[80:83], v[180:183], v[228:231], v[80:83]
	v_mfma_f32_16x16x32_bf16 v[68:71], v[188:191], v[228:231], v[68:71]
	s_setprio 0
	s_barrier
	s_add_i32 s24, s24, s20
	v_lshl_add_u64 v[192:193], s[14:15], 0, v[2:3]
	s_mov_b32 m0, s24
	ds_read_b128 v[200:203], v147 offset:16384
	ds_read_b128 v[204:207], v147 offset:17408
	ds_read_b128 v[208:211], v147 offset:18432
	ds_read_b128 v[212:215], v147 offset:19456
	ds_read_b128 v[216:219], v147 offset:20480
	ds_read_b128 v[220:223], v147 offset:21504
	ds_read_b128 v[224:227], v147 offset:22528
	ds_read_b128 v[228:231], v147 offset:23552
	global_load_lds_dwordx4 v[192:193], off
	s_add_i32 m0, s24, 0x2000
	s_add_u32 s64, s14, 0x40000
	v_lshl_add_u64 v[232:233], s[14:15], 0, v[0:1]
	s_addc_u32 s65, s15, 0
	s_add_i32 s24, s25, s20
	global_load_lds_dwordx4 v[232:233], off
	v_lshl_add_u64 v[234:235], s[64:65], 0, v[2:3]
	s_mov_b32 m0, s24
	v_lshl_add_u64 v[236:237], s[46:47], 0, v[132:133]
	global_load_lds_dwordx4 v[234:235], off
	v_lshl_add_u64 v[234:235], s[64:65], 0, v[0:1]
	s_add_i32 m0, s24, 0x2000
	s_nop 0
	global_load_lds_dwordx4 v[234:235], off
	v_lshl_add_u64 v[234:235], s[46:47], 0, v[134:135]
	s_mov_b32 m0, s21
	s_nop 0
	global_load_lds_dwordx4 v[234:235], off
	s_mov_b32 m0, s22
	s_nop 0
	global_load_lds_dwordx4 v[236:237], off
	s_waitcnt vmcnt(8)
	s_waitcnt lgkmcnt(0)
	s_barrier
	s_setprio 1
	s_waitcnt lgkmcnt(0)
	v_mfma_f32_16x16x32_bf16 v[60:63], v[140:143], v[200:203], 0
	v_mfma_f32_16x16x32_bf16 v[56:59], v[152:155], v[200:203], 0
	v_mfma_f32_16x16x32_bf16 v[44:47], v[140:143], v[208:211], 0
	v_mfma_f32_16x16x32_bf16 v[40:43], v[152:155], v[208:211], 0
	v_mfma_f32_16x16x32_bf16 v[28:31], v[140:143], v[216:219], 0
	v_mfma_f32_16x16x32_bf16 v[24:27], v[152:155], v[216:219], 0
	v_mfma_f32_16x16x32_bf16 v[12:15], v[140:143], v[224:227], 0
	v_mfma_f32_16x16x32_bf16 v[4:7], v[152:155], v[224:227], 0
	v_mfma_f32_16x16x32_bf16 v[60:63], v[148:151], v[204:207], v[60:63]
	v_mfma_f32_16x16x32_bf16 v[56:59], v[172:175], v[204:207], v[56:59]
	v_mfma_f32_16x16x32_bf16 v[44:47], v[148:151], v[212:215], v[44:47]
	v_mfma_f32_16x16x32_bf16 v[40:43], v[172:175], v[212:215], v[40:43]
	v_mfma_f32_16x16x32_bf16 v[28:31], v[148:151], v[220:223], v[28:31]
	v_mfma_f32_16x16x32_bf16 v[24:27], v[172:175], v[220:223], v[24:27]
	v_mfma_f32_16x16x32_bf16 v[12:15], v[148:151], v[228:231], v[12:15]
	v_mfma_f32_16x16x32_bf16 v[4:7], v[172:175], v[228:231], v[4:7]
	s_setprio 0
	s_setprio 1
	v_mfma_f32_16x16x32_bf16 v[64:67], v[176:179], v[200:203], 0
	v_mfma_f32_16x16x32_bf16 v[52:55], v[184:187], v[200:203], 0
	v_mfma_f32_16x16x32_bf16 v[48:51], v[176:179], v[208:211], 0
	v_mfma_f32_16x16x32_bf16 v[36:39], v[184:187], v[208:211], 0
	v_mfma_f32_16x16x32_bf16 v[32:35], v[176:179], v[216:219], 0
	v_mfma_f32_16x16x32_bf16 v[20:23], v[184:187], v[216:219], 0
	v_mfma_f32_16x16x32_bf16 v[16:19], v[176:179], v[224:227], 0
	v_mfma_f32_16x16x32_bf16 v[8:11], v[184:187], v[224:227], 0
	v_mfma_f32_16x16x32_bf16 v[64:67], v[180:183], v[204:207], v[64:67]
	v_mfma_f32_16x16x32_bf16 v[52:55], v[188:191], v[204:207], v[52:55]
	v_mfma_f32_16x16x32_bf16 v[48:51], v[180:183], v[212:215], v[48:51]
	v_mfma_f32_16x16x32_bf16 v[36:39], v[188:191], v[212:215], v[36:39]
	v_mfma_f32_16x16x32_bf16 v[32:35], v[180:183], v[220:223], v[32:35]
	v_mfma_f32_16x16x32_bf16 v[20:23], v[188:191], v[220:223], v[20:23]
	v_mfma_f32_16x16x32_bf16 v[16:19], v[180:183], v[228:231], v[16:19]
	v_mfma_f32_16x16x32_bf16 v[8:11], v[188:191], v[228:231], v[8:11]
	s_setprio 0
	s_barrier
	s_add_i32 s24, 0, 0x18000
	s_add_i32 s25, 0, 0x1c000
	v_add_u32_e32 v172, s24, v145
	v_add_u32_e32 v188, s25, v145
	ds_read_b128 v[140:143], v172
	ds_read_b128 v[148:151], v172 offset:1024
	ds_read_b128 v[152:155], v172 offset:2048
	ds_read_b128 v[172:175], v172 offset:3072
	ds_read_b128 v[176:179], v188
	ds_read_b128 v[180:183], v188 offset:1024
	ds_read_b128 v[184:187], v188 offset:2048
	ds_read_b128 v[188:191], v188 offset:3072
	s_add_u32 s46, s46, 0x40000
	s_addc_u32 s47, s47, 0
	s_mov_b32 m0, s23
	v_lshl_add_u64 v[238:239], s[46:47], 0, v[134:135]
	ds_read_b128 v[200:203], v147 offset:32768
	ds_read_b128 v[204:207], v147 offset:33792
	ds_read_b128 v[208:211], v147 offset:34816
	ds_read_b128 v[212:215], v147 offset:35840
	ds_read_b128 v[216:219], v147 offset:36864
	ds_read_b128 v[220:223], v147 offset:37888
	ds_read_b128 v[224:227], v147 offset:38912
	ds_read_b128 v[228:231], v147 offset:39936
	global_load_lds_dwordx4 v[238:239], off
	v_lshl_add_u64 v[238:239], s[46:47], 0, v[132:133]
	s_mov_b32 m0, s45
	s_nop 0
	global_load_lds_dwordx4 v[238:239], off
	s_waitcnt vmcnt(8)
	s_waitcnt lgkmcnt(0)
	s_barrier
	s_setprio 1
	s_waitcnt lgkmcnt(0)
	v_mfma_f32_16x16x32_bf16 v[124:127], v[140:143], v[200:203], v[124:127]
	v_mfma_f32_16x16x32_bf16 v[116:119], v[152:155], v[200:203], v[116:119]
	v_mfma_f32_16x16x32_bf16 v[108:111], v[140:143], v[208:211], v[108:111]
	v_mfma_f32_16x16x32_bf16 v[104:107], v[152:155], v[208:211], v[104:107]
	v_mfma_f32_16x16x32_bf16 v[92:95], v[140:143], v[216:219], v[92:95]
	v_mfma_f32_16x16x32_bf16 v[88:91], v[152:155], v[216:219], v[88:91]
	v_mfma_f32_16x16x32_bf16 v[76:79], v[140:143], v[224:227], v[76:79]
	v_mfma_f32_16x16x32_bf16 v[72:75], v[152:155], v[224:227], v[72:75]
	v_mfma_f32_16x16x32_bf16 v[124:127], v[148:151], v[204:207], v[124:127]
	v_mfma_f32_16x16x32_bf16 v[116:119], v[172:175], v[204:207], v[116:119]
	v_mfma_f32_16x16x32_bf16 v[108:111], v[148:151], v[212:215], v[108:111]
	v_mfma_f32_16x16x32_bf16 v[104:107], v[172:175], v[212:215], v[104:107]
	v_mfma_f32_16x16x32_bf16 v[92:95], v[148:151], v[220:223], v[92:95]
	v_mfma_f32_16x16x32_bf16 v[88:91], v[172:175], v[220:223], v[88:91]
	v_mfma_f32_16x16x32_bf16 v[76:79], v[148:151], v[228:231], v[76:79]
	v_mfma_f32_16x16x32_bf16 v[72:75], v[172:175], v[228:231], v[72:75]
	s_setprio 0
	s_setprio 1
	v_mfma_f32_16x16x32_bf16 v[128:131], v[176:179], v[200:203], v[128:131]
	v_mfma_f32_16x16x32_bf16 v[120:123], v[184:187], v[200:203], v[120:123]
	v_mfma_f32_16x16x32_bf16 v[112:115], v[176:179], v[208:211], v[112:115]
	v_mfma_f32_16x16x32_bf16 v[100:103], v[184:187], v[208:211], v[100:103]
	v_mfma_f32_16x16x32_bf16 v[96:99], v[176:179], v[216:219], v[96:99]
	v_mfma_f32_16x16x32_bf16 v[84:87], v[184:187], v[216:219], v[84:87]
	v_mfma_f32_16x16x32_bf16 v[80:83], v[176:179], v[224:227], v[80:83]
	v_mfma_f32_16x16x32_bf16 v[68:71], v[184:187], v[224:227], v[68:71]
	v_mfma_f32_16x16x32_bf16 v[128:131], v[180:183], v[204:207], v[128:131]
	v_mfma_f32_16x16x32_bf16 v[120:123], v[188:191], v[204:207], v[120:123]
	v_mfma_f32_16x16x32_bf16 v[112:115], v[180:183], v[212:215], v[112:115]
	v_mfma_f32_16x16x32_bf16 v[100:103], v[188:191], v[212:215], v[100:103]
	v_mfma_f32_16x16x32_bf16 v[96:99], v[180:183], v[220:223], v[96:99]
	v_mfma_f32_16x16x32_bf16 v[84:87], v[188:191], v[220:223], v[84:87]
	v_mfma_f32_16x16x32_bf16 v[80:83], v[180:183], v[228:231], v[80:83]
	v_mfma_f32_16x16x32_bf16 v[68:71], v[188:191], v[228:231], v[68:71]
	s_setprio 0
	s_barrier
	s_add_i32 s24, s24, s20
	v_lshl_add_u64 v[192:193], v[192:193], 0, s[26:27]
	s_mov_b32 m0, s24
	ds_read_b128 v[200:203], v147 offset:49152
	ds_read_b128 v[204:207], v147 offset:50176
	ds_read_b128 v[208:211], v147 offset:51200
	ds_read_b128 v[212:215], v147 offset:52224
	ds_read_b128 v[216:219], v147 offset:53248
	ds_read_b128 v[220:223], v147 offset:54272
	ds_read_b128 v[224:227], v147 offset:55296
	ds_read_b128 v[228:231], v147 offset:56320
	global_load_lds_dwordx4 v[192:193], off
	s_add_i32 m0, s24, 0x2000
	s_add_u32 s14, s14, 0x40080
	v_lshl_add_u64 v[192:193], v[232:233], 0, s[26:27]
	s_addc_u32 s15, s15, 0
	s_add_i32 s24, s25, s20
	global_load_lds_dwordx4 v[192:193], off
	v_lshl_add_u64 v[192:193], s[14:15], 0, v[2:3]
	s_mov_b32 m0, s24
	s_nop 0
	global_load_lds_dwordx4 v[192:193], off
	v_lshl_add_u64 v[192:193], s[14:15], 0, v[0:1]
	s_add_i32 m0, s24, 0x2000
	s_nop 0
	global_load_lds_dwordx4 v[192:193], off
	v_lshl_add_u64 v[192:193], v[234:235], 0, s[26:27]
	s_mov_b32 m0, s36
	s_nop 0
	global_load_lds_dwordx4 v[192:193], off
	v_lshl_add_u64 v[192:193], v[236:237], 0, s[26:27]
	s_mov_b32 m0, s48
	s_nop 0
	global_load_lds_dwordx4 v[192:193], off
	s_waitcnt vmcnt(8)
	s_waitcnt lgkmcnt(0)
	s_barrier
	s_setprio 1
	s_waitcnt lgkmcnt(0)
	v_mfma_f32_16x16x32_bf16 v[60:63], v[140:143], v[200:203], v[60:63]
	v_mfma_f32_16x16x32_bf16 v[56:59], v[152:155], v[200:203], v[56:59]
	v_mfma_f32_16x16x32_bf16 v[44:47], v[140:143], v[208:211], v[44:47]
	v_mfma_f32_16x16x32_bf16 v[40:43], v[152:155], v[208:211], v[40:43]
	v_mfma_f32_16x16x32_bf16 v[28:31], v[140:143], v[216:219], v[28:31]
	v_mfma_f32_16x16x32_bf16 v[24:27], v[152:155], v[216:219], v[24:27]
	v_mfma_f32_16x16x32_bf16 v[12:15], v[140:143], v[224:227], v[12:15]
	v_mfma_f32_16x16x32_bf16 v[4:7], v[152:155], v[224:227], v[4:7]
	v_mfma_f32_16x16x32_bf16 v[60:63], v[148:151], v[204:207], v[60:63]
	v_mfma_f32_16x16x32_bf16 v[56:59], v[172:175], v[204:207], v[56:59]
	v_mfma_f32_16x16x32_bf16 v[44:47], v[148:151], v[212:215], v[44:47]
	v_mfma_f32_16x16x32_bf16 v[40:43], v[172:175], v[212:215], v[40:43]
	v_mfma_f32_16x16x32_bf16 v[28:31], v[148:151], v[220:223], v[28:31]
	v_mfma_f32_16x16x32_bf16 v[24:27], v[172:175], v[220:223], v[24:27]
	v_mfma_f32_16x16x32_bf16 v[12:15], v[148:151], v[228:231], v[12:15]
	v_mfma_f32_16x16x32_bf16 v[4:7], v[172:175], v[228:231], v[4:7]
	s_setprio 0
	s_setprio 1
	v_mfma_f32_16x16x32_bf16 v[64:67], v[176:179], v[200:203], v[64:67]
	v_mfma_f32_16x16x32_bf16 v[52:55], v[184:187], v[200:203], v[52:55]
	v_mfma_f32_16x16x32_bf16 v[48:51], v[176:179], v[208:211], v[48:51]
	v_mfma_f32_16x16x32_bf16 v[36:39], v[184:187], v[208:211], v[36:39]
	v_mfma_f32_16x16x32_bf16 v[32:35], v[176:179], v[216:219], v[32:35]
	v_mfma_f32_16x16x32_bf16 v[20:23], v[184:187], v[216:219], v[20:23]
	v_mfma_f32_16x16x32_bf16 v[16:19], v[176:179], v[224:227], v[16:19]
	v_mfma_f32_16x16x32_bf16 v[8:11], v[184:187], v[224:227], v[8:11]
	v_mfma_f32_16x16x32_bf16 v[64:67], v[180:183], v[204:207], v[64:67]
	v_mfma_f32_16x16x32_bf16 v[52:55], v[188:191], v[204:207], v[52:55]
	v_mfma_f32_16x16x32_bf16 v[48:51], v[180:183], v[212:215], v[48:51]
	v_mfma_f32_16x16x32_bf16 v[36:39], v[188:191], v[212:215], v[36:39]
	v_mfma_f32_16x16x32_bf16 v[32:35], v[180:183], v[220:223], v[32:35]
	v_mfma_f32_16x16x32_bf16 v[20:23], v[188:191], v[220:223], v[20:23]
	v_mfma_f32_16x16x32_bf16 v[16:19], v[180:183], v[228:231], v[16:19]
	v_mfma_f32_16x16x32_bf16 v[8:11], v[188:191], v[228:231], v[8:11]
	s_setprio 0
	s_barrier
	s_add_i32 s63, s63, 2
	s_add_u32 s60, s60, 0x100
	s_addc_u32 s61, s61, 0
	s_add_u32 s42, s42, 0x100
	s_addc_u32 s43, s43, 0
	s_cmp_gt_u32 s63, 13
	s_cbranch_scc0 .LBB0_960
	s_branch .Lpeel_exit_G3

.Lpeel_exit_G3:
	s_and_b64 vcc, exec, s[10:11]
	s_cbranch_vccz .LBB0_963
	s_barrier
